# MLP-down K-loop: nt on the A-operand (HB, streamed once) LDS-DMA loads
# baseline (speedup 1.0000x reference)
; #define PG8_STAGE(bufoff, gbase, voff) do { _Pragma("unroll") for (int _i = 0; _i < 2; ++_i) \
;         __builtin_amdgcn_global_load_lds((const unsigned*)((const char*)(gbase) + (voff)[_i]), (PG8_LAS unsigned*)(lds + (bufoff) + ldsw + _i * 8192), 16, 0, 0); } while (0)
; #define PG8_LDA(dst, b, h) do { _Pragma("unroll") for (int m = 0; m < 4; ++m) _Pragma("unroll") for (int k = 0; k < 2; ++k) dst[m][k] = *(const PG8_LAS bf16x8*)(lds + PG8_SA(b, h) + aoff + m * 2048 + k * 1024); } while (0)
; #define PG8_LDB(dst, b, h) do { _Pragma("unroll") for (int n = 0; n < 2; ++n) _Pragma("unroll") for (int k = 0; k < 2; ++k) dst[n][k] = *(const PG8_LAS bf16x8*)(lds + PG8_SB(b, h) + boff + n * 2048 + k * 1024); } while (0)
; #define PG8_MMA(ai, bj, At, Bt) do { __builtin_amdgcn_s_setprio(1); _Pragma("unroll") for (int m = 0; m < 4; ++m) _Pragma("unroll") for (int n = 0; n < 2; ++n) _Pragma("unroll") for (int k = 0; k < 2; ++k) \
;         acc[ai][bj][m][n] = __builtin_amdgcn_mfma_f32_16x16x32_bf16(Bt[n][k], At[m][k], acc[ai][bj][m][n], 0, 0, 0); __builtin_amdgcn_s_setprio(0); } while (0)
; #define PG8_WAIT_L(n) asm volatile("s_waitcnt lgkmcnt(" #n ")" ::: "memory")
; #define PG8_WAIT_V8_UNLESS(flag) asm volatile("s_cmp_lg_i32 %0, 0\n\ts_cbranch_scc1 .Lpg8rx%=\n\ts_waitcnt vmcnt(8)\n.Lpg8rx%=:" :: "s"(__builtin_amdgcn_readfirstlane(flag)) : "scc", "memory")
; #define PG8_BAR __builtin_amdgcn_s_barrier()
; #define PG8_SCHED __builtin_amdgcn_sched_barrier(0)
; template <class Epi, class Sched, bool ALIGN_EPI = false, bool SP2 = false>
; __device__ __forceinline__ void gemm_phase(PG8_LAS unsigned char* lds, const Gemm g, const Sched& S, const Epi& E) {
;     ...
;             PG8_STAGE(PG8_SA(1, 1), a1 + hstep, voffA); PG8_SCHED; PG8_LDB(B0, 0, 0); PG8_LDB(B1, 0, 1); PG8_SCHED; PG8_LDA(At, 0, 0);
;             PG8_WAIT_V8_UNLESS(rx); PG8_WAIT_L(0); PG8_BAR; PG8_MMA(0, 0, At, B0); PG8_MMA(0, 1, At, B1); PG8_BAR; PG8_SCHED;
;             PG8_STAGE(PG8_SB(0, 0), b2, voffB); PG8_STAGE(PG8_SB(0, 1), b2 + hstep, voffB); PG8_STAGE(PG8_SA(0, 0), a2, voffA); PG8_SCHED; PG8_LDA(At, 0, 1);
;             PG8_WAIT_V8_UNLESS(rx); PG8_WAIT_L(0); PG8_BAR; PG8_MMA(1, 0, At, B0); PG8_MMA(1, 1, At, B1); PG8_BAR; PG8_SCHED;
.LBB0_965:
	s_add_u32 s28, s0, s40
	s_addc_u32 s29, s1, s41
	s_add_u32 s30, s28, 0x100
	s_addc_u32 s31, s29, 0
	s_add_u32 s98, s28, 0x100080
	s_addc_u32 s99, s29, 0
	s_add_u32 s57, s54, s40
	s_addc_u32 s60, s55, s41
	s_cmp_eq_u32 s40, 0
	s_cselect_b64 s[28:29], -1, 0
	s_and_b64 s[58:59], s[26:27], s[28:29]
	s_cmpk_eq_i32 s40, 0x1f00
	s_cselect_b32 s31, s15, s31
	s_cselect_b32 s30, s23, s30
	s_cselect_b32 s29, s13, s60
	s_cselect_b32 s28, s53, s57
	s_add_i32 s57, 0, 0x10000
	s_add_i32 s60, 0, 0x14000
	v_add_u32_e32 v136, s57, v247
	v_add_u32_e32 v160, s60, v247
	ds_read_b128 v[120:123], v136
	ds_read_b128 v[128:131], v136 offset:1024
	ds_read_b128 v[132:135], v136 offset:2048
	ds_read_b128 v[136:139], v136 offset:3072
	ds_read_b128 v[140:143], v160
	ds_read_b128 v[144:147], v160 offset:1024
	ds_read_b128 v[156:159], v160 offset:2048
	ds_read_b128 v[160:163], v160 offset:3072
	ds_read_b128 v[164:167], v248
	ds_read_b128 v[168:171], v248 offset:1024
	ds_read_b128 v[172:175], v248 offset:2048
	ds_read_b128 v[176:179], v248 offset:3072
	ds_read_b128 v[180:183], v248 offset:4096
	ds_read_b128 v[184:187], v248 offset:5120
	ds_read_b128 v[188:191], v248 offset:6144
	ds_read_b128 v[214:217], v248 offset:7168
	s_add_i32 m0, s25, 0xc000
	s_and_b32 s61, s58, 1
	global_load_lds_dwordx4 v204, s[98:99] nt
	s_add_i32 m0, s25, 0xe000
	s_nop 0
	global_load_lds_dwordx4 v206, s[98:99] nt
	s_cmp_lg_i32 s61, 0
	s_cbranch_scc1 .Lpg8rx6
	s_waitcnt vmcnt(8)
.Lpg8rx6:
	s_waitcnt lgkmcnt(0)
	s_setprio 1
	s_barrier
	v_mfma_f32_16x16x32_bf16 v[152:155], v[120:123], v[164:167], v[152:155]
	v_mfma_f32_16x16x32_bf16 v[148:151], v[132:135], v[164:167], v[148:151]
	v_mfma_f32_16x16x32_bf16 v[108:111], v[120:123], v[172:175], v[108:111]
	v_mfma_f32_16x16x32_bf16 v[104:107], v[132:135], v[172:175], v[104:107]
	v_mfma_f32_16x16x32_bf16 v[92:95], v[120:123], v[180:183], v[92:95]
	v_mfma_f32_16x16x32_bf16 v[88:91], v[132:135], v[180:183], v[88:91]
	v_mfma_f32_16x16x32_bf16 v[76:79], v[120:123], v[188:191], v[76:79]
	v_mfma_f32_16x16x32_bf16 v[72:75], v[132:135], v[188:191], v[72:75]
	v_mfma_f32_16x16x32_bf16 v[152:155], v[128:131], v[168:171], v[152:155]
	v_mfma_f32_16x16x32_bf16 v[148:151], v[136:139], v[168:171], v[148:151]
	v_mfma_f32_16x16x32_bf16 v[108:111], v[128:131], v[176:179], v[108:111]
	v_mfma_f32_16x16x32_bf16 v[104:107], v[136:139], v[176:179], v[104:107]
	v_mfma_f32_16x16x32_bf16 v[92:95], v[128:131], v[184:187], v[92:95]
	v_mfma_f32_16x16x32_bf16 v[88:91], v[136:139], v[184:187], v[88:91]
	v_mfma_f32_16x16x32_bf16 v[76:79], v[128:131], v[214:217], v[76:79]
	v_mfma_f32_16x16x32_bf16 v[72:75], v[136:139], v[214:217], v[72:75]
	v_mfma_f32_16x16x32_bf16 v[124:127], v[140:143], v[164:167], v[124:127]
	v_mfma_f32_16x16x32_bf16 v[112:115], v[156:159], v[164:167], v[112:115]
	v_mfma_f32_16x16x32_bf16 v[100:103], v[140:143], v[172:175], v[100:103]
	v_mfma_f32_16x16x32_bf16 v[96:99], v[156:159], v[172:175], v[96:99]
	v_mfma_f32_16x16x32_bf16 v[84:87], v[140:143], v[180:183], v[84:87]
	v_mfma_f32_16x16x32_bf16 v[80:83], v[156:159], v[180:183], v[80:83]
	v_mfma_f32_16x16x32_bf16 v[68:71], v[140:143], v[188:191], v[68:71]
	v_mfma_f32_16x16x32_bf16 v[64:67], v[156:159], v[188:191], v[64:67]
	v_mfma_f32_16x16x32_bf16 v[124:127], v[144:147], v[168:171], v[124:127]
	v_mfma_f32_16x16x32_bf16 v[112:115], v[160:163], v[168:171], v[112:115]
	v_mfma_f32_16x16x32_bf16 v[100:103], v[144:147], v[176:179], v[100:103]
	v_mfma_f32_16x16x32_bf16 v[96:99], v[160:163], v[176:179], v[96:99]
	v_mfma_f32_16x16x32_bf16 v[84:87], v[144:147], v[184:187], v[84:87]
	v_mfma_f32_16x16x32_bf16 v[80:83], v[160:163], v[184:187], v[80:83]
	v_mfma_f32_16x16x32_bf16 v[68:71], v[144:147], v[214:217], v[68:71]
	v_mfma_f32_16x16x32_bf16 v[64:67], v[160:163], v[214:217], v[64:67]
	s_setprio 0
	s_barrier
	ds_read_b128 v[164:167], v248 offset:16384
	ds_read_b128 v[168:171], v248 offset:17408
	ds_read_b128 v[172:175], v248 offset:18432
	ds_read_b128 v[176:179], v248 offset:19456
	ds_read_b128 v[180:183], v248 offset:20480
	ds_read_b128 v[184:187], v248 offset:21504
	ds_read_b128 v[188:191], v248 offset:22528
	ds_read_b128 v[214:217], v248 offset:23552
	s_add_u32 s58, s28, 0x100000
	s_addc_u32 s59, s29, 0
	s_add_i32 m0, s57, s39
	s_nop 0
	global_load_lds_dwordx4 v194, s[28:29]
	s_add_i32 m0, m0, 0x2000
	s_nop 0
	global_load_lds_dwordx4 v208, s[28:29]
	s_add_i32 m0, s60, s39
	s_nop 0
	global_load_lds_dwordx4 v194, s[58:59]
	s_add_i32 m0, m0, 0x2000
	s_nop 0
	global_load_lds_dwordx4 v208, s[58:59]
	s_mov_b32 m0, s25
	s_nop 0
	global_load_lds_dwordx4 v204, s[30:31] nt
	s_mov_b32 m0, s42
	s_nop 0
	global_load_lds_dwordx4 v206, s[30:31] nt
	s_cmp_lg_i32 s61, 0
	s_cbranch_scc1 .Lpg8rx7
	s_waitcnt vmcnt(8)
; #define PG8_STAGE(bufoff, gbase, voff) do { _Pragma("unroll") for (int _i = 0; _i < 2; ++_i) \
;         __builtin_amdgcn_global_load_lds((const unsigned*)((const char*)(gbase) + (voff)[_i]), (PG8_LAS unsigned*)(lds + (bufoff) + ldsw + _i * 8192), 16, 0, 0); } while (0)
; #define PG8_LDA(dst, b, h) do { _Pragma("unroll") for (int m = 0; m < 4; ++m) _Pragma("unroll") for (int k = 0; k < 2; ++k) dst[m][k] = *(const PG8_LAS bf16x8*)(lds + PG8_SA(b, h) + aoff + m * 2048 + k * 1024); } while (0)
; #define PG8_LDB(dst, b, h) do { _Pragma("unroll") for (int n = 0; n < 2; ++n) _Pragma("unroll") for (int k = 0; k < 2; ++k) dst[n][k] = *(const PG8_LAS bf16x8*)(lds + PG8_SB(b, h) + boff + n * 2048 + k * 1024); } while (0)
; #define PG8_MMA(ai, bj, At, Bt) do { __builtin_amdgcn_s_setprio(1); _Pragma("unroll") for (int m = 0; m < 4; ++m) _Pragma("unroll") for (int n = 0; n < 2; ++n) _Pragma("unroll") for (int k = 0; k < 2; ++k) \
;         acc[ai][bj][m][n] = __builtin_amdgcn_mfma_f32_16x16x32_bf16(Bt[n][k], At[m][k], acc[ai][bj][m][n], 0, 0, 0); __builtin_amdgcn_s_setprio(0); } while (0)
; #define PG8_WAIT_V(n) asm volatile("s_waitcnt vmcnt(" #n ")" ::: "memory")
; #define PG8_WAIT_L(n) asm volatile("s_waitcnt lgkmcnt(" #n ")" ::: "memory")
; #define PG8_BAR __builtin_amdgcn_s_barrier()
; #define PG8_SCHED __builtin_amdgcn_sched_barrier(0)
; template <class Epi, class Sched, bool ALIGN_EPI = false, bool SP2 = false>
; __device__ __forceinline__ void gemm_phase(PG8_LAS unsigned char* lds, const Gemm g, const Sched& S, const Epi& E) {
;     ...
;             PG8_STAGE(PG8_SA(0, 1), a2 + hstep, voffA); PG8_SCHED; PG8_LDB(B0, 1, 0); PG8_LDB(B1, 1, 1); PG8_SCHED; PG8_LDA(At, 1, 0);
;             PG8_WAIT_V(8); PG8_WAIT_L(0); PG8_BAR; PG8_MMA(0, 0, At, B0); PG8_MMA(0, 1, At, B1); PG8_BAR; PG8_SCHED;
.Lpg8rx7:
	s_waitcnt lgkmcnt(0)
	s_setprio 1
	s_barrier
	v_mfma_f32_16x16x32_bf16 v[60:63], v[120:123], v[164:167], v[60:63]
	v_mfma_f32_16x16x32_bf16 v[56:59], v[132:135], v[164:167], v[56:59]
	v_mfma_f32_16x16x32_bf16 v[44:47], v[120:123], v[172:175], v[44:47]
	v_mfma_f32_16x16x32_bf16 v[40:43], v[132:135], v[172:175], v[40:43]
	v_mfma_f32_16x16x32_bf16 v[28:31], v[120:123], v[180:183], v[28:31]
	v_mfma_f32_16x16x32_bf16 v[24:27], v[132:135], v[180:183], v[24:27]
	v_mfma_f32_16x16x32_bf16 v[12:15], v[120:123], v[188:191], v[12:15]
	v_mfma_f32_16x16x32_bf16 v[8:11], v[132:135], v[188:191], v[8:11]
	v_mfma_f32_16x16x32_bf16 v[60:63], v[128:131], v[168:171], v[60:63]
	v_mfma_f32_16x16x32_bf16 v[56:59], v[136:139], v[168:171], v[56:59]
	v_mfma_f32_16x16x32_bf16 v[44:47], v[128:131], v[176:179], v[44:47]
	v_mfma_f32_16x16x32_bf16 v[40:43], v[136:139], v[176:179], v[40:43]
	v_mfma_f32_16x16x32_bf16 v[28:31], v[128:131], v[184:187], v[28:31]
	v_mfma_f32_16x16x32_bf16 v[24:27], v[136:139], v[184:187], v[24:27]
	v_mfma_f32_16x16x32_bf16 v[12:15], v[128:131], v[214:217], v[12:15]
	v_mfma_f32_16x16x32_bf16 v[8:11], v[136:139], v[214:217], v[8:11]
	v_mfma_f32_16x16x32_bf16 v[52:55], v[140:143], v[164:167], v[52:55]
	v_mfma_f32_16x16x32_bf16 v[48:51], v[156:159], v[164:167], v[48:51]
	v_mfma_f32_16x16x32_bf16 v[36:39], v[140:143], v[172:175], v[36:39]
	v_mfma_f32_16x16x32_bf16 v[32:35], v[156:159], v[172:175], v[32:35]
	v_mfma_f32_16x16x32_bf16 v[20:23], v[140:143], v[180:183], v[20:23]
	v_mfma_f32_16x16x32_bf16 v[16:19], v[156:159], v[180:183], v[16:19]
	v_mfma_f32_16x16x32_bf16 v[4:7], v[140:143], v[188:191], v[4:7]
	v_mfma_f32_16x16x32_bf16 v[0:3], v[156:159], v[188:191], v[0:3]
	v_mfma_f32_16x16x32_bf16 v[52:55], v[144:147], v[168:171], v[52:55]
	v_mfma_f32_16x16x32_bf16 v[48:51], v[160:163], v[168:171], v[48:51]
	v_mfma_f32_16x16x32_bf16 v[36:39], v[144:147], v[176:179], v[36:39]
	v_mfma_f32_16x16x32_bf16 v[32:35], v[160:163], v[176:179], v[32:35]
	v_mfma_f32_16x16x32_bf16 v[20:23], v[144:147], v[184:187], v[20:23]
	v_mfma_f32_16x16x32_bf16 v[16:19], v[160:163], v[184:187], v[16:19]
	v_mfma_f32_16x16x32_bf16 v[4:7], v[144:147], v[214:217], v[4:7]
	v_mfma_f32_16x16x32_bf16 v[0:3], v[160:163], v[214:217], v[0:3]
	s_setprio 0
	s_barrier
	s_mov_b64 s[98:99], s[30:31]
	s_add_u32 s100, s30, 0x100000
	s_addc_u32 s101, s31, 0
	s_add_i32 s30, 0, 0x18000
	s_add_i32 s31, 0, 0x1c000
	v_add_u32_e32 v136, s30, v247
	v_add_u32_e32 v160, s31, v247
	ds_read_b128 v[120:123], v136
	ds_read_b128 v[128:131], v136 offset:1024
	ds_read_b128 v[132:135], v136 offset:2048
	ds_read_b128 v[136:139], v136 offset:3072
	ds_read_b128 v[140:143], v160
	ds_read_b128 v[144:147], v160 offset:1024
	ds_read_b128 v[156:159], v160 offset:2048
	ds_read_b128 v[160:163], v160 offset:3072
	ds_read_b128 v[164:167], v248 offset:32768
	ds_read_b128 v[168:171], v248 offset:33792
	ds_read_b128 v[172:175], v248 offset:34816
	ds_read_b128 v[176:179], v248 offset:35840
	ds_read_b128 v[180:183], v248 offset:36864
	ds_read_b128 v[184:187], v248 offset:37888
	ds_read_b128 v[188:191], v248 offset:38912
	ds_read_b128 v[214:217], v248 offset:39936
	s_mov_b32 m0, s43
	s_nop 0
	global_load_lds_dwordx4 v204, s[100:101] nt
	s_mov_b32 m0, s44
	s_nop 0
	global_load_lds_dwordx4 v206, s[100:101] nt
	s_waitcnt vmcnt(8)
	s_waitcnt lgkmcnt(0)
	s_setprio 1
	s_barrier
	v_mfma_f32_16x16x32_bf16 v[152:155], v[120:123], v[164:167], v[152:155]
	v_mfma_f32_16x16x32_bf16 v[148:151], v[132:135], v[164:167], v[148:151]
	v_mfma_f32_16x16x32_bf16 v[108:111], v[120:123], v[172:175], v[108:111]
	v_mfma_f32_16x16x32_bf16 v[104:107], v[132:135], v[172:175], v[104:107]
	v_mfma_f32_16x16x32_bf16 v[92:95], v[120:123], v[180:183], v[92:95]
	v_mfma_f32_16x16x32_bf16 v[88:91], v[132:135], v[180:183], v[88:91]
	v_mfma_f32_16x16x32_bf16 v[76:79], v[120:123], v[188:191], v[76:79]
	v_mfma_f32_16x16x32_bf16 v[72:75], v[132:135], v[188:191], v[72:75]
	v_mfma_f32_16x16x32_bf16 v[152:155], v[128:131], v[168:171], v[152:155]
	v_mfma_f32_16x16x32_bf16 v[148:151], v[136:139], v[168:171], v[148:151]
	v_mfma_f32_16x16x32_bf16 v[108:111], v[128:131], v[176:179], v[108:111]
	v_mfma_f32_16x16x32_bf16 v[104:107], v[136:139], v[176:179], v[104:107]
	v_mfma_f32_16x16x32_bf16 v[92:95], v[128:131], v[184:187], v[92:95]
	v_mfma_f32_16x16x32_bf16 v[88:91], v[136:139], v[184:187], v[88:91]
	v_mfma_f32_16x16x32_bf16 v[76:79], v[128:131], v[214:217], v[76:79]
	v_mfma_f32_16x16x32_bf16 v[72:75], v[136:139], v[214:217], v[72:75]
	v_mfma_f32_16x16x32_bf16 v[124:127], v[140:143], v[164:167], v[124:127]
	v_mfma_f32_16x16x32_bf16 v[112:115], v[156:159], v[164:167], v[112:115]
	v_mfma_f32_16x16x32_bf16 v[100:103], v[140:143], v[172:175], v[100:103]
	v_mfma_f32_16x16x32_bf16 v[96:99], v[156:159], v[172:175], v[96:99]
	v_mfma_f32_16x16x32_bf16 v[84:87], v[140:143], v[180:183], v[84:87]
	v_mfma_f32_16x16x32_bf16 v[80:83], v[156:159], v[180:183], v[80:83]
	v_mfma_f32_16x16x32_bf16 v[68:71], v[140:143], v[188:191], v[68:71]
	v_mfma_f32_16x16x32_bf16 v[64:67], v[156:159], v[188:191], v[64:67]
	v_mfma_f32_16x16x32_bf16 v[124:127], v[144:147], v[168:171], v[124:127]
	v_mfma_f32_16x16x32_bf16 v[112:115], v[160:163], v[168:171], v[112:115]
	v_mfma_f32_16x16x32_bf16 v[100:103], v[144:147], v[176:179], v[100:103]
	v_mfma_f32_16x16x32_bf16 v[96:99], v[160:163], v[176:179], v[96:99]
	v_mfma_f32_16x16x32_bf16 v[84:87], v[144:147], v[184:187], v[84:87]
	v_mfma_f32_16x16x32_bf16 v[80:83], v[160:163], v[184:187], v[80:83]
	v_mfma_f32_16x16x32_bf16 v[68:71], v[144:147], v[214:217], v[68:71]
	v_mfma_f32_16x16x32_bf16 v[64:67], v[160:163], v[214:217], v[64:67]
	s_setprio 0
	s_barrier
; #define PG8_STAGE(bufoff, gbase, voff) do { _Pragma("unroll") for (int _i = 0; _i < 2; ++_i) \
;         __builtin_amdgcn_global_load_lds((const unsigned*)((const char*)(gbase) + (voff)[_i]), (PG8_LAS unsigned*)(lds + (bufoff) + ldsw + _i * 8192), 16, 0, 0); } while (0)
; #define PG8_LDA(dst, b, h) do { _Pragma("unroll") for (int m = 0; m < 4; ++m) _Pragma("unroll") for (int k = 0; k < 2; ++k) dst[m][k] = *(const PG8_LAS bf16x8*)(lds + PG8_SA(b, h) + aoff + m * 2048 + k * 1024); } while (0)
; #define PG8_MMA(ai, bj, At, Bt) do { __builtin_amdgcn_s_setprio(1); _Pragma("unroll") for (int m = 0; m < 4; ++m) _Pragma("unroll") for (int n = 0; n < 2; ++n) _Pragma("unroll") for (int k = 0; k < 2; ++k) \
;         acc[ai][bj][m][n] = __builtin_amdgcn_mfma_f32_16x16x32_bf16(Bt[n][k], At[m][k], acc[ai][bj][m][n], 0, 0, 0); __builtin_amdgcn_s_setprio(0); } while (0)
; #define PG8_WAIT_V(n) asm volatile("s_waitcnt vmcnt(" #n ")" ::: "memory")
; #define PG8_WAIT_L(n) asm volatile("s_waitcnt lgkmcnt(" #n ")" ::: "memory")
; #define PG8_BAR __builtin_amdgcn_s_barrier()
; #define PG8_SCHED __builtin_amdgcn_sched_barrier(0)
; template <class Epi, class Sched, bool ALIGN_EPI = false, bool SP2 = false>
; __device__ __forceinline__ void gemm_phase(PG8_LAS unsigned char* lds, const Gemm g, const Sched& S, const Epi& E) {
;     ...
;         for (int t = 0; t < nt; t += 2) {
;     ...
;             PG8_STAGE(PG8_SB(1, 0), b3, voffB); PG8_STAGE(PG8_SB(1, 1), b3 + hstep, voffB); PG8_STAGE(PG8_SA(1, 0), a3, voffA); PG8_SCHED; PG8_LDA(At, 1, 1);
;             PG8_WAIT_V(8); PG8_WAIT_L(0); PG8_BAR; PG8_MMA(1, 0, At, B0); PG8_MMA(1, 1, At, B1); PG8_BAR; PG8_SCHED;
	ds_read_b128 v[164:167], v248 offset:49152
	ds_read_b128 v[168:171], v248 offset:50176
	ds_read_b128 v[172:175], v248 offset:51200
	ds_read_b128 v[176:179], v248 offset:52224
	ds_read_b128 v[180:183], v248 offset:53248
	ds_read_b128 v[184:187], v248 offset:54272
	ds_read_b128 v[188:191], v248 offset:55296
	ds_read_b128 v[214:217], v248 offset:56320
	s_add_u32 s100, s28, 0x80
	s_addc_u32 s101, s29, 0
	s_add_u32 s28, s28, 0x100080
	s_addc_u32 s29, s29, 0
	s_add_u32 s98, s98, 0x80
	s_addc_u32 s99, s99, 0
	s_add_i32 m0, s30, s39
	s_nop 0
	global_load_lds_dwordx4 v194, s[100:101]
	s_add_i32 m0, m0, 0x2000
	s_nop 0
	global_load_lds_dwordx4 v208, s[100:101]
	s_add_i32 m0, s31, s39
	s_nop 0
	global_load_lds_dwordx4 v194, s[28:29]
	s_add_i32 m0, m0, 0x2000
	s_nop 0
	global_load_lds_dwordx4 v208, s[28:29]
	s_mov_b32 m0, s46
	s_nop 0
	global_load_lds_dwordx4 v204, s[98:99] nt
	s_mov_b32 m0, s48
	s_nop 0
	global_load_lds_dwordx4 v206, s[98:99] nt
	s_waitcnt vmcnt(8)
	s_waitcnt lgkmcnt(0)
	s_setprio 1
	s_barrier
	v_mfma_f32_16x16x32_bf16 v[60:63], v[120:123], v[164:167], v[60:63]
	v_mfma_f32_16x16x32_bf16 v[56:59], v[132:135], v[164:167], v[56:59]
	v_mfma_f32_16x16x32_bf16 v[44:47], v[120:123], v[172:175], v[44:47]
	v_mfma_f32_16x16x32_bf16 v[40:43], v[132:135], v[172:175], v[40:43]
	v_mfma_f32_16x16x32_bf16 v[28:31], v[120:123], v[180:183], v[28:31]
	v_mfma_f32_16x16x32_bf16 v[24:27], v[132:135], v[180:183], v[24:27]
	v_mfma_f32_16x16x32_bf16 v[12:15], v[120:123], v[188:191], v[12:15]
	v_mfma_f32_16x16x32_bf16 v[8:11], v[132:135], v[188:191], v[8:11]
	v_mfma_f32_16x16x32_bf16 v[60:63], v[128:131], v[168:171], v[60:63]
	v_mfma_f32_16x16x32_bf16 v[56:59], v[136:139], v[168:171], v[56:59]
	v_mfma_f32_16x16x32_bf16 v[44:47], v[128:131], v[176:179], v[44:47]
	v_mfma_f32_16x16x32_bf16 v[40:43], v[136:139], v[176:179], v[40:43]
	v_mfma_f32_16x16x32_bf16 v[28:31], v[128:131], v[184:187], v[28:31]
	v_mfma_f32_16x16x32_bf16 v[24:27], v[136:139], v[184:187], v[24:27]
	v_mfma_f32_16x16x32_bf16 v[12:15], v[128:131], v[214:217], v[12:15]
	v_mfma_f32_16x16x32_bf16 v[8:11], v[136:139], v[214:217], v[8:11]
	v_mfma_f32_16x16x32_bf16 v[52:55], v[140:143], v[164:167], v[52:55]
	v_mfma_f32_16x16x32_bf16 v[48:51], v[156:159], v[164:167], v[48:51]
	v_mfma_f32_16x16x32_bf16 v[36:39], v[140:143], v[172:175], v[36:39]
	v_mfma_f32_16x16x32_bf16 v[32:35], v[156:159], v[172:175], v[32:35]
	v_mfma_f32_16x16x32_bf16 v[20:23], v[140:143], v[180:183], v[20:23]
	v_mfma_f32_16x16x32_bf16 v[16:19], v[156:159], v[180:183], v[16:19]
	v_mfma_f32_16x16x32_bf16 v[4:7], v[140:143], v[188:191], v[4:7]
	v_mfma_f32_16x16x32_bf16 v[0:3], v[156:159], v[188:191], v[0:3]
	v_mfma_f32_16x16x32_bf16 v[52:55], v[144:147], v[168:171], v[52:55]
	v_mfma_f32_16x16x32_bf16 v[48:51], v[160:163], v[168:171], v[48:51]
	v_mfma_f32_16x16x32_bf16 v[36:39], v[144:147], v[176:179], v[36:39]
	v_mfma_f32_16x16x32_bf16 v[32:35], v[160:163], v[176:179], v[32:35]
	v_mfma_f32_16x16x32_bf16 v[20:23], v[144:147], v[184:187], v[20:23]
	v_mfma_f32_16x16x32_bf16 v[16:19], v[160:163], v[184:187], v[16:19]
	v_mfma_f32_16x16x32_bf16 v[4:7], v[144:147], v[214:217], v[4:7]
	v_mfma_f32_16x16x32_bf16 v[0:3], v[160:163], v[214:217], v[0:3]
	s_setprio 0
	s_barrier
	s_add_i32 s56, s56, 2
	s_add_u32 s40, s40, 0x100
	s_addc_u32 s41, s41, 0
	s_cmp_gt_u32 s56, 61
	s_cbranch_scc0 .LBB0_965
	s_and_b64 vcc, exec, s[10:11]
	s_cbranch_vccz .LBB0_968
	s_barrier
